# k64 + first K-iteration after an epilogue peeled with vmcnt(24) in phases 1 and 2 (P8, P1): the next tile starts while the epilogue stores drain
# speedup vs baseline: 1.0045x; 1.0002x over previous
.LBB0_184:
	s_cmp_lt_i32 s82, 2
	s_cselect_b64 s[0:1], -1, 0
	s_cmp_gt_i32 s83, 1
	s_cselect_b64 s[2:3], -1, 0
	s_and_b64 s[0:1], s[0:1], s[2:3]
	s_andn2_b64 vcc, exec, s[0:1]
	s_cbranch_vccnz .LBB0_315
	s_mov_b32 s97, 0
	s_cmpk_lt_i32 s67, 0xc00
	s_cselect_b64 s[0:1], -1, 0
	s_cmpk_gt_i32 s67, 0xbff
	s_mov_b32 s33, -1
	s_load_dwordx2 s[4:5], s[92:93], 0xb8
	s_waitcnt lgkmcnt(0)
	v_mbcnt_lo_u32_b32 v0, -1, 0
	v_mbcnt_hi_u32_b32 v0, -1, v0
	s_cbranch_scc1 .LBB0_187
	s_ashr_i32 s2, s67, 31
	s_lshr_b32 s2, s2, 29
	s_add_i32 s2, s67, s2
	s_ashr_i32 s3, s2, 3
	s_and_b32 s2, s2, -8
	s_sub_i32 s2, s67, s2
	s_cmp_lt_i32 s2, 0
	s_movk_i32 s6, 0x181
	s_cselect_b32 s6, s6, 0x180
	s_mul_i32 s2, s2, s6
	s_add_i32 s2, s2, s3
	s_mul_hi_i32 s3, s2, 0x2aaaaaab
	s_lshr_b32 s6, s3, 31
	s_ashr_i32 s3, s3, 6
	s_add_i32 s3, s3, s6
	s_lshl_b32 s6, s3, 3
	s_mulk_i32 s3, 0x180
	s_sub_i32 s2, s2, s3
	s_bfe_u32 s3, s2, 0x3001c
	s_add_i32 s3, s2, s3
	s_and_b32 s3, s3, 0xfff8
	s_sub_i32 s2, s2, s3
	s_sext_i32_i16 s2, s2
	s_add_i32 s33, s6, s2

.LBB0_199:
	s_ashr_i32 s17, s16, 31
	s_lshl_b64 s[18:19], s[16:17], 21
	s_add_u32 s18, s37, s18
	s_addc_u32 s19, s38, s19
	s_and_b64 s[20:21], s[4:5], exec
	s_cselect_b32 s17, s19, s7
	s_cselect_b32 s23, s18, s6
	s_ashr_i32 s15, s14, 31
	s_lshl_b64 s[20:21], s[14:15], 21
	s_add_u32 s20, s39, s20
	s_addc_u32 s21, s40, s21
	s_and_b64 s[28:29], s[4:5], exec
	s_cselect_b32 s15, s21, s27
	s_cselect_b32 s25, s20, s26
	s_add_u32 s6, s6, 0x100800
	s_addc_u32 s7, s7, 0
	s_add_u32 s30, s26, 0x1000
	v_mov_b32_e32 v0, 0
	s_addc_u32 s31, s27, 0
	s_mov_b32 s34, -2
	s_waitcnt lgkmcnt(0)
	v_mov_b32_e32 v1, v0
	v_mov_b32_e32 v2, v0
	v_mov_b32_e32 v3, v0
	v_mov_b32_e32 v4, v0
	v_mov_b32_e32 v5, v0
	v_mov_b32_e32 v6, v0
	v_mov_b32_e32 v7, v0
	v_mov_b32_e32 v8, v0
	v_mov_b32_e32 v9, v0
	v_mov_b32_e32 v10, v0
	v_mov_b32_e32 v11, v0
	v_mov_b32_e32 v12, v0
	v_mov_b32_e32 v13, v0
	v_mov_b32_e32 v14, v0
	v_mov_b32_e32 v15, v0
	v_mov_b32_e32 v16, v0
	v_mov_b32_e32 v17, v0
	v_mov_b32_e32 v18, v0
	v_mov_b32_e32 v19, v0
	v_mov_b32_e32 v20, v0
	v_mov_b32_e32 v21, v0
	v_mov_b32_e32 v22, v0
	v_mov_b32_e32 v23, v0
	v_mov_b32_e32 v24, v0
	v_mov_b32_e32 v25, v0
	v_mov_b32_e32 v26, v0
	v_mov_b32_e32 v27, v0
	v_mov_b32_e32 v28, v0
	v_mov_b32_e32 v29, v0
	v_mov_b32_e32 v30, v0
	v_mov_b32_e32 v31, v0
	v_mov_b32_e32 v64, v0
	v_mov_b32_e32 v65, v0
	v_mov_b32_e32 v66, v0
	v_mov_b32_e32 v67, v0
	v_mov_b32_e32 v68, v0
	v_mov_b32_e32 v69, v0
	v_mov_b32_e32 v70, v0
	v_mov_b32_e32 v71, v0
	v_mov_b32_e32 v72, v0
	v_mov_b32_e32 v73, v0
	v_mov_b32_e32 v74, v0
	v_mov_b32_e32 v75, v0
	v_mov_b32_e32 v76, v0
	v_mov_b32_e32 v77, v0
	v_mov_b32_e32 v78, v0
	v_mov_b32_e32 v79, v0
	v_mov_b32_e32 v80, v0
	v_mov_b32_e32 v81, v0
	v_mov_b32_e32 v82, v0
	v_mov_b32_e32 v83, v0
	v_mov_b32_e32 v84, v0
	v_mov_b32_e32 v85, v0
	v_mov_b32_e32 v86, v0
	v_mov_b32_e32 v87, v0
	v_mov_b32_e32 v88, v0
	v_mov_b32_e32 v89, v0
	v_mov_b32_e32 v90, v0
	v_mov_b32_e32 v91, v0
	v_mov_b32_e32 v92, v0
	v_mov_b32_e32 v93, v0
	v_mov_b32_e32 v94, v0
	v_mov_b32_e32 v95, v0
	v_mov_b32_e32 v32, v0
	v_mov_b32_e32 v33, v0
	v_mov_b32_e32 v34, v0
	v_mov_b32_e32 v35, v0
	v_mov_b32_e32 v36, v0
	v_mov_b32_e32 v37, v0
	v_mov_b32_e32 v38, v0
	v_mov_b32_e32 v39, v0
	v_mov_b32_e32 v40, v0
	v_mov_b32_e32 v41, v0
	v_mov_b32_e32 v42, v0
	v_mov_b32_e32 v43, v0
	v_mov_b32_e32 v44, v0
	v_mov_b32_e32 v45, v0
	v_mov_b32_e32 v46, v0
	v_mov_b32_e32 v47, v0
	v_mov_b32_e32 v48, v0
	v_mov_b32_e32 v49, v0
	v_mov_b32_e32 v50, v0
	v_mov_b32_e32 v51, v0
	v_mov_b32_e32 v52, v0
	v_mov_b32_e32 v53, v0
	v_mov_b32_e32 v54, v0
	v_mov_b32_e32 v55, v0
	v_mov_b32_e32 v56, v0
	v_mov_b32_e32 v57, v0
	v_mov_b32_e32 v58, v0
	v_mov_b32_e32 v59, v0
	v_mov_b32_e32 v60, v0
	v_mov_b32_e32 v61, v0
	v_mov_b32_e32 v62, v0
	v_mov_b32_e32 v63, v0
	v_mov_b32_e32 v96, v0
	v_mov_b32_e32 v97, v0
	v_mov_b32_e32 v98, v0
	v_mov_b32_e32 v99, v0
	v_mov_b32_e32 v100, v0
	v_mov_b32_e32 v101, v0
	v_mov_b32_e32 v102, v0
	v_mov_b32_e32 v103, v0
	v_mov_b32_e32 v104, v0
	v_mov_b32_e32 v105, v0
	v_mov_b32_e32 v106, v0
	v_mov_b32_e32 v107, v0
	v_mov_b32_e32 v108, v0
	v_mov_b32_e32 v109, v0
	v_mov_b32_e32 v110, v0
	v_mov_b32_e32 v111, v0
	v_mov_b32_e32 v112, v0
	v_mov_b32_e32 v113, v0
	v_mov_b32_e32 v114, v0
	v_mov_b32_e32 v115, v0
	v_mov_b32_e32 v116, v0
	v_mov_b32_e32 v117, v0
	v_mov_b32_e32 v118, v0
	v_mov_b32_e32 v119, v0
	v_mov_b32_e32 v120, v0
	v_mov_b32_e32 v121, v0
	v_mov_b32_e32 v122, v0
	v_mov_b32_e32 v123, v0
	v_mov_b32_e32 v124, v0
	v_mov_b32_e32 v125, v0
	v_mov_b32_e32 v126, v0
	v_mov_b32_e32 v127, v0
	s_cmp_eq_u32 s97, 0
	s_cbranch_scc1 .LBB0_200
	ds_read_b128 v[148:151], v169
	ds_read_b128 v[152:155], v169 offset:1024
	ds_read_b128 v[156:159], v169 offset:2048
	ds_read_b128 v[160:163], v169 offset:3072
	ds_read_b128 v[174:177], v170
	ds_read_b128 v[178:181], v170 offset:1024
	ds_read_b128 v[182:185], v170 offset:2048
	ds_read_b128 v[186:189], v170 offset:3072
	s_add_u32 s26, s6, 0xfff00800
	s_addc_u32 s27, s7, -1
	s_cmp_eq_u32 s34, 60
	s_cselect_b32 s29, s17, s27
	s_cselect_b32 s28, s23, s26
	s_cselect_b32 s27, s15, s31
	s_cselect_b32 s26, s25, s30
	v_lshl_add_u64 v[190:191], s[6:7], 0, v[138:139]
	s_add_i32 m0, s41, 0xc000
	s_nop 0
	global_load_lds_dwordx4 v[190:191], off
	v_lshl_add_u64 v[190:191], s[6:7], 0, v[140:141]
	s_add_i32 m0, s41, 0xe000
	s_nop 0
	global_load_lds_dwordx4 v[190:191], off
	ds_read_b128 v[190:193], v171
	ds_read_b128 v[194:197], v171 offset:1024
	ds_read_b128 v[198:201], v171 offset:2048
	ds_read_b128 v[202:205], v171 offset:3072
	ds_read_b128 v[206:209], v171 offset:4096
	ds_read_b128 v[210:213], v171 offset:5120
	ds_read_b128 v[214:217], v171 offset:6144
	ds_read_b128 v[218:221], v171 offset:7168
	s_waitcnt vmcnt(24)
	s_waitcnt lgkmcnt(0)
	s_barrier
	v_mfma_f32_16x16x32_bf16 v[124:127], v[148:151], v[190:193], v[124:127]
	v_mfma_f32_16x16x32_bf16 v[124:127], v[152:155], v[194:197], v[124:127]
	v_mfma_f32_16x16x32_bf16 v[120:123], v[160:163], v[194:197], v[120:123]
	v_mfma_f32_16x16x32_bf16 v[120:123], v[156:159], v[190:193], v[120:123]
	v_mfma_f32_16x16x32_bf16 v[60:63], v[174:177], v[190:193], v[60:63]
	v_mfma_f32_16x16x32_bf16 v[60:63], v[178:181], v[194:197], v[60:63]
	v_mfma_f32_16x16x32_bf16 v[56:59], v[186:189], v[194:197], v[56:59]
	v_mfma_f32_16x16x32_bf16 v[56:59], v[182:185], v[190:193], v[56:59]
	v_mfma_f32_16x16x32_bf16 v[48:51], v[182:185], v[198:201], v[48:51]
	v_mfma_f32_16x16x32_bf16 v[48:51], v[186:189], v[202:205], v[48:51]
	v_mfma_f32_16x16x32_bf16 v[52:55], v[178:181], v[202:205], v[52:55]
	v_mfma_f32_16x16x32_bf16 v[52:55], v[174:177], v[198:201], v[52:55]
	v_mfma_f32_16x16x32_bf16 v[112:115], v[156:159], v[198:201], v[112:115]
	v_mfma_f32_16x16x32_bf16 v[112:115], v[160:163], v[202:205], v[112:115]
	v_mfma_f32_16x16x32_bf16 v[116:119], v[152:155], v[202:205], v[116:119]
	v_mfma_f32_16x16x32_bf16 v[116:119], v[148:151], v[198:201], v[116:119]
	v_mfma_f32_16x16x32_bf16 v[108:111], v[148:151], v[206:209], v[108:111]
	v_mfma_f32_16x16x32_bf16 v[108:111], v[152:155], v[210:213], v[108:111]
	v_mfma_f32_16x16x32_bf16 v[104:107], v[160:163], v[210:213], v[104:107]
	v_mfma_f32_16x16x32_bf16 v[104:107], v[156:159], v[206:209], v[104:107]
	v_mfma_f32_16x16x32_bf16 v[44:47], v[174:177], v[206:209], v[44:47]
	v_mfma_f32_16x16x32_bf16 v[44:47], v[178:181], v[210:213], v[44:47]
	v_mfma_f32_16x16x32_bf16 v[40:43], v[186:189], v[210:213], v[40:43]
	v_mfma_f32_16x16x32_bf16 v[40:43], v[182:185], v[206:209], v[40:43]
	v_mfma_f32_16x16x32_bf16 v[32:35], v[182:185], v[214:217], v[32:35]
	v_mfma_f32_16x16x32_bf16 v[32:35], v[186:189], v[218:221], v[32:35]
	v_mfma_f32_16x16x32_bf16 v[36:39], v[178:181], v[218:221], v[36:39]
	v_mfma_f32_16x16x32_bf16 v[36:39], v[174:177], v[214:217], v[36:39]
	v_mfma_f32_16x16x32_bf16 v[96:99], v[156:159], v[214:217], v[96:99]
	v_mfma_f32_16x16x32_bf16 v[96:99], v[160:163], v[218:221], v[96:99]
	v_mfma_f32_16x16x32_bf16 v[100:103], v[152:155], v[218:221], v[100:103]
	v_mfma_f32_16x16x32_bf16 v[100:103], v[148:151], v[214:217], v[100:103]
	s_barrier
	s_add_i32 s35, s55, s36
	v_lshl_add_u64 v[222:223], s[26:27], 0, v[130:131]
	s_mov_b32 m0, s35
	v_lshl_add_u64 v[224:225], s[26:27], 0, v[134:135]
	global_load_lds_dwordx4 v[222:223], off
	s_add_i32 m0, s35, 0x2000
	s_add_u32 s58, s26, 0x100000
	s_addc_u32 s59, s27, 0
	s_add_i32 s35, s56, s36
	global_load_lds_dwordx4 v[224:225], off
	v_lshl_add_u64 v[190:191], s[58:59], 0, v[130:131]
	s_mov_b32 m0, s35
	v_lshl_add_u64 v[226:227], s[28:29], 0, v[128:129]
	global_load_lds_dwordx4 v[190:191], off
	v_lshl_add_u64 v[190:191], s[58:59], 0, v[134:135]
	s_add_i32 m0, s35, 0x2000
	v_lshl_add_u64 v[228:229], s[28:29], 0, v[132:133]
	global_load_lds_dwordx4 v[190:191], off
	s_mov_b32 m0, s41
	s_nop 0
	global_load_lds_dwordx4 v[226:227], off
	s_mov_b32 m0, s42
	s_nop 0
	global_load_lds_dwordx4 v[228:229], off
	ds_read_b128 v[190:193], v171 offset:16384
	ds_read_b128 v[194:197], v171 offset:17408
	ds_read_b128 v[198:201], v171 offset:18432
	ds_read_b128 v[202:205], v171 offset:19456
	ds_read_b128 v[206:209], v171 offset:20480
	ds_read_b128 v[210:213], v171 offset:21504
	ds_read_b128 v[214:217], v171 offset:22528
	ds_read_b128 v[218:221], v171 offset:23552
	s_waitcnt vmcnt(24)
	s_waitcnt lgkmcnt(0)
	s_barrier
	v_mfma_f32_16x16x32_bf16 v[92:95], v[148:151], v[190:193], v[92:95]
	v_mfma_f32_16x16x32_bf16 v[92:95], v[152:155], v[194:197], v[92:95]
	v_mfma_f32_16x16x32_bf16 v[88:91], v[160:163], v[194:197], v[88:91]
	v_mfma_f32_16x16x32_bf16 v[88:91], v[156:159], v[190:193], v[88:91]
	v_mfma_f32_16x16x32_bf16 v[28:31], v[174:177], v[190:193], v[28:31]
	v_mfma_f32_16x16x32_bf16 v[28:31], v[178:181], v[194:197], v[28:31]
	v_mfma_f32_16x16x32_bf16 v[24:27], v[186:189], v[194:197], v[24:27]
	v_mfma_f32_16x16x32_bf16 v[24:27], v[182:185], v[190:193], v[24:27]
	v_mfma_f32_16x16x32_bf16 v[16:19], v[182:185], v[198:201], v[16:19]
	v_mfma_f32_16x16x32_bf16 v[16:19], v[186:189], v[202:205], v[16:19]
	v_mfma_f32_16x16x32_bf16 v[20:23], v[178:181], v[202:205], v[20:23]
	v_mfma_f32_16x16x32_bf16 v[20:23], v[174:177], v[198:201], v[20:23]
	v_mfma_f32_16x16x32_bf16 v[80:83], v[156:159], v[198:201], v[80:83]
	v_mfma_f32_16x16x32_bf16 v[80:83], v[160:163], v[202:205], v[80:83]
	v_mfma_f32_16x16x32_bf16 v[84:87], v[152:155], v[202:205], v[84:87]
	v_mfma_f32_16x16x32_bf16 v[84:87], v[148:151], v[198:201], v[84:87]
	v_mfma_f32_16x16x32_bf16 v[76:79], v[148:151], v[206:209], v[76:79]
	v_mfma_f32_16x16x32_bf16 v[76:79], v[152:155], v[210:213], v[76:79]
	v_mfma_f32_16x16x32_bf16 v[72:75], v[160:163], v[210:213], v[72:75]
	v_mfma_f32_16x16x32_bf16 v[72:75], v[156:159], v[206:209], v[72:75]
	v_mfma_f32_16x16x32_bf16 v[12:15], v[174:177], v[206:209], v[12:15]
	v_mfma_f32_16x16x32_bf16 v[12:15], v[178:181], v[210:213], v[12:15]
	v_mfma_f32_16x16x32_bf16 v[8:11], v[186:189], v[210:213], v[8:11]
	v_mfma_f32_16x16x32_bf16 v[8:11], v[182:185], v[206:209], v[8:11]
	v_mfma_f32_16x16x32_bf16 v[0:3], v[182:185], v[214:217], v[0:3]
	v_mfma_f32_16x16x32_bf16 v[0:3], v[186:189], v[218:221], v[0:3]
	v_mfma_f32_16x16x32_bf16 v[4:7], v[178:181], v[218:221], v[4:7]
	v_mfma_f32_16x16x32_bf16 v[4:7], v[174:177], v[214:217], v[4:7]
	v_mfma_f32_16x16x32_bf16 v[64:67], v[156:159], v[214:217], v[64:67]
	v_mfma_f32_16x16x32_bf16 v[64:67], v[160:163], v[218:221], v[64:67]
	v_mfma_f32_16x16x32_bf16 v[68:71], v[152:155], v[218:221], v[68:71]
	v_mfma_f32_16x16x32_bf16 v[68:71], v[148:151], v[214:217], v[68:71]
	s_barrier
	s_add_i32 s35, 0, 0x18000
	v_add_u32_e32 v136, s35, v165
	s_add_i32 s57, 0, 0x1c000
	ds_read_b128 v[148:151], v136
	ds_read_b128 v[152:155], v136 offset:1024
	ds_read_b128 v[156:159], v136 offset:2048
	ds_read_b128 v[160:163], v136 offset:3072
	v_add_u32_e32 v136, s57, v165
	ds_read_b128 v[174:177], v136
	ds_read_b128 v[178:181], v136 offset:1024
	ds_read_b128 v[182:185], v136 offset:2048
	ds_read_b128 v[186:189], v136 offset:3072
	s_add_u32 s28, s28, 0x100000
	s_addc_u32 s29, s29, 0
	s_mov_b32 m0, s43
	v_lshl_add_u64 v[190:191], s[28:29], 0, v[128:129]
	global_load_lds_dwordx4 v[190:191], off
	v_lshl_add_u64 v[190:191], s[28:29], 0, v[132:133]
	s_mov_b32 m0, s44
	s_nop 0
	global_load_lds_dwordx4 v[190:191], off
	ds_read_b128 v[190:193], v171 offset:32768
	ds_read_b128 v[194:197], v171 offset:33792
	ds_read_b128 v[198:201], v171 offset:34816
	ds_read_b128 v[202:205], v171 offset:35840
	ds_read_b128 v[206:209], v171 offset:36864
	ds_read_b128 v[210:213], v171 offset:37888
	ds_read_b128 v[214:217], v171 offset:38912
	ds_read_b128 v[218:221], v171 offset:39936
	s_waitcnt vmcnt(8)
	s_waitcnt lgkmcnt(0)
	s_barrier
	v_mfma_f32_16x16x32_bf16 v[124:127], v[148:151], v[190:193], v[124:127]
	v_mfma_f32_16x16x32_bf16 v[124:127], v[152:155], v[194:197], v[124:127]
	v_mfma_f32_16x16x32_bf16 v[120:123], v[160:163], v[194:197], v[120:123]
	v_mfma_f32_16x16x32_bf16 v[120:123], v[156:159], v[190:193], v[120:123]
	v_mfma_f32_16x16x32_bf16 v[60:63], v[174:177], v[190:193], v[60:63]
	v_mfma_f32_16x16x32_bf16 v[60:63], v[178:181], v[194:197], v[60:63]
	v_mfma_f32_16x16x32_bf16 v[56:59], v[186:189], v[194:197], v[56:59]
	v_mfma_f32_16x16x32_bf16 v[56:59], v[182:185], v[190:193], v[56:59]
	v_mfma_f32_16x16x32_bf16 v[48:51], v[182:185], v[198:201], v[48:51]
	v_mfma_f32_16x16x32_bf16 v[48:51], v[186:189], v[202:205], v[48:51]
	v_mfma_f32_16x16x32_bf16 v[52:55], v[178:181], v[202:205], v[52:55]
	v_mfma_f32_16x16x32_bf16 v[52:55], v[174:177], v[198:201], v[52:55]
	v_mfma_f32_16x16x32_bf16 v[112:115], v[156:159], v[198:201], v[112:115]
	v_mfma_f32_16x16x32_bf16 v[112:115], v[160:163], v[202:205], v[112:115]
	v_mfma_f32_16x16x32_bf16 v[116:119], v[152:155], v[202:205], v[116:119]
	v_mfma_f32_16x16x32_bf16 v[116:119], v[148:151], v[198:201], v[116:119]
	v_mfma_f32_16x16x32_bf16 v[108:111], v[148:151], v[206:209], v[108:111]
	v_mfma_f32_16x16x32_bf16 v[108:111], v[152:155], v[210:213], v[108:111]
	v_mfma_f32_16x16x32_bf16 v[104:107], v[160:163], v[210:213], v[104:107]
	v_mfma_f32_16x16x32_bf16 v[104:107], v[156:159], v[206:209], v[104:107]
	v_mfma_f32_16x16x32_bf16 v[44:47], v[174:177], v[206:209], v[44:47]
	v_mfma_f32_16x16x32_bf16 v[44:47], v[178:181], v[210:213], v[44:47]
	v_mfma_f32_16x16x32_bf16 v[40:43], v[186:189], v[210:213], v[40:43]
	v_mfma_f32_16x16x32_bf16 v[40:43], v[182:185], v[206:209], v[40:43]
	v_mfma_f32_16x16x32_bf16 v[32:35], v[182:185], v[214:217], v[32:35]
	v_mfma_f32_16x16x32_bf16 v[32:35], v[186:189], v[218:221], v[32:35]
	v_mfma_f32_16x16x32_bf16 v[36:39], v[178:181], v[218:221], v[36:39]
	v_mfma_f32_16x16x32_bf16 v[36:39], v[174:177], v[214:217], v[36:39]
	v_mfma_f32_16x16x32_bf16 v[96:99], v[156:159], v[214:217], v[96:99]
	v_mfma_f32_16x16x32_bf16 v[96:99], v[160:163], v[218:221], v[96:99]
	v_mfma_f32_16x16x32_bf16 v[100:103], v[152:155], v[218:221], v[100:103]
	v_mfma_f32_16x16x32_bf16 v[100:103], v[148:151], v[214:217], v[100:103]
	s_barrier
	s_add_i32 s28, s35, s36
	v_lshl_add_u64 v[190:191], v[222:223], 0, s[12:13]
	s_mov_b32 m0, s28
	s_nop 0
	global_load_lds_dwordx4 v[190:191], off
	s_add_i32 m0, s28, 0x2000
	s_add_u32 s26, s26, 0x100800
	v_lshl_add_u64 v[190:191], v[224:225], 0, s[12:13]
	s_addc_u32 s27, s27, 0
	s_add_i32 s28, s57, s36
	global_load_lds_dwordx4 v[190:191], off
	v_lshl_add_u64 v[190:191], s[26:27], 0, v[130:131]
	s_mov_b32 m0, s28
	s_nop 0
	global_load_lds_dwordx4 v[190:191], off
	v_lshl_add_u64 v[190:191], s[26:27], 0, v[134:135]
	s_add_i32 m0, s28, 0x2000
	s_nop 0
	global_load_lds_dwordx4 v[190:191], off
	v_lshl_add_u64 v[190:191], v[226:227], 0, s[12:13]
	s_mov_b32 m0, s49
	s_nop 0
	global_load_lds_dwordx4 v[190:191], off
	v_lshl_add_u64 v[190:191], v[228:229], 0, s[12:13]
	s_mov_b32 m0, s50
	s_nop 0
	global_load_lds_dwordx4 v[190:191], off
	ds_read_b128 v[190:193], v171 offset:49152
	ds_read_b128 v[194:197], v171 offset:50176
	ds_read_b128 v[198:201], v171 offset:51200
	ds_read_b128 v[202:205], v171 offset:52224
	ds_read_b128 v[206:209], v171 offset:53248
	ds_read_b128 v[210:213], v171 offset:54272
	ds_read_b128 v[214:217], v171 offset:55296
	ds_read_b128 v[218:221], v171 offset:56320
	s_waitcnt vmcnt(8)
	s_waitcnt lgkmcnt(0)
	s_barrier
	v_mfma_f32_16x16x32_bf16 v[92:95], v[148:151], v[190:193], v[92:95]
	v_mfma_f32_16x16x32_bf16 v[92:95], v[152:155], v[194:197], v[92:95]
	v_mfma_f32_16x16x32_bf16 v[88:91], v[160:163], v[194:197], v[88:91]
	v_mfma_f32_16x16x32_bf16 v[88:91], v[156:159], v[190:193], v[88:91]
	v_mfma_f32_16x16x32_bf16 v[28:31], v[174:177], v[190:193], v[28:31]
	v_mfma_f32_16x16x32_bf16 v[28:31], v[178:181], v[194:197], v[28:31]
	v_mfma_f32_16x16x32_bf16 v[24:27], v[186:189], v[194:197], v[24:27]
	v_mfma_f32_16x16x32_bf16 v[24:27], v[182:185], v[190:193], v[24:27]
	v_mfma_f32_16x16x32_bf16 v[16:19], v[182:185], v[198:201], v[16:19]
	v_mfma_f32_16x16x32_bf16 v[16:19], v[186:189], v[202:205], v[16:19]
	v_mfma_f32_16x16x32_bf16 v[20:23], v[178:181], v[202:205], v[20:23]
	v_mfma_f32_16x16x32_bf16 v[20:23], v[174:177], v[198:201], v[20:23]
	v_mfma_f32_16x16x32_bf16 v[80:83], v[156:159], v[198:201], v[80:83]
	v_mfma_f32_16x16x32_bf16 v[80:83], v[160:163], v[202:205], v[80:83]
	v_mfma_f32_16x16x32_bf16 v[84:87], v[152:155], v[202:205], v[84:87]
	v_mfma_f32_16x16x32_bf16 v[84:87], v[148:151], v[198:201], v[84:87]
	v_mfma_f32_16x16x32_bf16 v[76:79], v[148:151], v[206:209], v[76:79]
	v_mfma_f32_16x16x32_bf16 v[76:79], v[152:155], v[210:213], v[76:79]
	v_mfma_f32_16x16x32_bf16 v[72:75], v[160:163], v[210:213], v[72:75]
	v_mfma_f32_16x16x32_bf16 v[72:75], v[156:159], v[206:209], v[72:75]
	v_mfma_f32_16x16x32_bf16 v[12:15], v[174:177], v[206:209], v[12:15]
	v_mfma_f32_16x16x32_bf16 v[12:15], v[178:181], v[210:213], v[12:15]
	v_mfma_f32_16x16x32_bf16 v[8:11], v[186:189], v[210:213], v[8:11]
	v_mfma_f32_16x16x32_bf16 v[8:11], v[182:185], v[206:209], v[8:11]
	v_mfma_f32_16x16x32_bf16 v[0:3], v[182:185], v[214:217], v[0:3]
	v_mfma_f32_16x16x32_bf16 v[0:3], v[186:189], v[218:221], v[0:3]
	v_mfma_f32_16x16x32_bf16 v[4:7], v[178:181], v[218:221], v[4:7]
	v_mfma_f32_16x16x32_bf16 v[4:7], v[174:177], v[214:217], v[4:7]
	v_mfma_f32_16x16x32_bf16 v[64:67], v[156:159], v[214:217], v[64:67]
	v_mfma_f32_16x16x32_bf16 v[64:67], v[160:163], v[218:221], v[64:67]
	v_mfma_f32_16x16x32_bf16 v[68:71], v[152:155], v[218:221], v[68:71]
	v_mfma_f32_16x16x32_bf16 v[68:71], v[148:151], v[214:217], v[68:71]
	s_barrier
	s_add_i32 s34, s34, 2
	s_add_u32 s6, s6, 0x1000
	s_addc_u32 s7, s7, 0
	s_add_u32 s30, s30, 0x1000
	s_addc_u32 s31, s31, 0
	s_cmp_gt_u32 s34, 61
	s_cbranch_scc1 .Lpeel_exit_P1

.Lpeel_exit_P1:
.LBB0_203:
	s_cmp_lg_u32 s22, s33
	s_cselect_b64 s[26:27], -1, 0
	v_lshl_or_b32 v148, s22, 8, v168
	s_mov_b64 s[6:7], -1
	s_and_b64 vcc, exec, s[26:27]
	s_cbranch_vccz .LBB0_205
	v_ashrrev_i32_e32 v149, 31, v148
	v_lshl_add_u64 v[150:151], v[148:149], 2, s[10:11]
	global_load_dword v150, v[150:151], off
	s_mov_b64 s[6:7], 0

.Lepibar_P1:
	s_mov_b32 s97, 1
	v_pk_mul_f32 v[162:163], v[34:35], v[156:157] op_sel_hi:[1,0]
	v_pk_mul_f32 v[174:175], v[32:33], v[156:157] op_sel_hi:[1,0]
	v_pk_mul_f32 v[160:161], v[36:37], v[156:157] op_sel_hi:[1,0]
	v_pk_mul_f32 v[158:159], v[38:39], v[156:157] op_sel_hi:[1,0]
	v_cvt_pk_bf16_f32 v156, v160, v161
	v_lshl_add_u64 v[160:161], s[30:31], 0, v[136:137]
	v_lshl_add_u64 v[160:161], v[160:161], 0, v[146:147]
	v_cvt_pk_bf16_f32 v157, v158, v159
	v_cvt_pk_bf16_f32 v158, v174, v175
	v_cvt_pk_bf16_f32 v159, v162, v163
	global_store_dwordx4 v[160:161], v[156:159], off
	s_and_b64 vcc, exec, s[6:7]
	s_mov_b64 s[34:35], -1
	v_or_b32_e32 v156, 0x80, v148
	s_cbranch_vccnz .LBB0_221
	v_ashrrev_i32_e32 v157, 31, v156
	v_lshl_add_u64 v[158:159], v[156:157], 2, s[10:11]
	global_load_dword v158, v[158:159], off
	s_mov_b64 s[34:35], 0

.LBB0_1515:
	s_cmp_lt_i32 s82, 9
	s_cselect_b64 s[0:1], -1, 0
	s_cmp_gt_i32 s83, 8
	s_cselect_b64 s[2:3], -1, 0
	s_and_b64 s[0:1], s[0:1], s[2:3]
	s_andn2_b64 vcc, exec, s[0:1]
	s_cbranch_vccnz .LBB0_1608
	s_mov_b32 s97, 0
	s_cmpk_lt_i32 s67, 0x1000
	s_cselect_b64 s[2:3], -1, 0
	s_cmpk_gt_i32 s67, 0xfff
	s_mov_b32 s28, -1
	s_load_dwordx2 s[0:1], s[92:93], 0xb8
	s_waitcnt lgkmcnt(0)
	s_waitcnt lgkmcnt(0)
	v_mbcnt_lo_u32_b32 v1, -1, 0
	v_mbcnt_hi_u32_b32 v1, -1, v1
	s_cbranch_scc1 .LBB0_1522
	s_ashr_i32 s4, s67, 31
	s_lshr_b32 s4, s4, 29
	s_add_i32 s6, s67, s4
	s_and_b32 s4, s6, -8
	s_sub_i32 s7, s67, s4
	s_cmp_gt_i32 s7, -1
	s_cbranch_scc0 .LBB0_1519
	s_lshl_b32 s8, s7, 9
	s_cbranch_execz .LBB0_1520
	s_branch .LBB0_1521

.LBB0_1542:
	s_ashr_i32 s13, s12, 31
	s_lshl_b64 s[14:15], s[12:13], 21
	s_add_u32 s14, s31, s14
	s_addc_u32 s15, s33, s15
	s_and_b64 s[16:17], s[2:3], exec
	s_cselect_b32 s13, s15, s21
	s_cselect_b32 s50, s14, s20
	s_ashr_i32 s11, s10, 31
	s_lshl_b64 s[16:17], s[10:11], 21
	s_add_u32 s16, s34, s16
	s_addc_u32 s17, s35, s17
	s_and_b64 s[24:25], s[2:3], exec
	s_cselect_b32 s11, s17, s23
	s_cselect_b32 s51, s16, s22
	s_add_u32 s52, s22, 0x1000
	v_mov_b32_e32 v0, 0
	s_addc_u32 s53, s23, 0
	s_mov_b32 s54, -2
	v_mov_b32_e32 v1, v0
	v_mov_b32_e32 v2, v0
	v_mov_b32_e32 v3, v0
	v_mov_b32_e32 v4, v0
	v_mov_b32_e32 v5, v0
	v_mov_b32_e32 v6, v0
	v_mov_b32_e32 v7, v0
	v_mov_b32_e32 v16, v0
	v_mov_b32_e32 v17, v0
	v_mov_b32_e32 v18, v0
	v_mov_b32_e32 v19, v0
	v_mov_b32_e32 v20, v0
	v_mov_b32_e32 v21, v0
	v_mov_b32_e32 v22, v0
	v_mov_b32_e32 v23, v0
	v_mov_b32_e32 v32, v0
	v_mov_b32_e32 v33, v0
	v_mov_b32_e32 v34, v0
	v_mov_b32_e32 v35, v0
	v_mov_b32_e32 v36, v0
	v_mov_b32_e32 v37, v0
	v_mov_b32_e32 v38, v0
	v_mov_b32_e32 v39, v0
	v_mov_b32_e32 v48, v0
	v_mov_b32_e32 v49, v0
	v_mov_b32_e32 v50, v0
	v_mov_b32_e32 v51, v0
	v_mov_b32_e32 v52, v0
	v_mov_b32_e32 v53, v0
	v_mov_b32_e32 v54, v0
	v_mov_b32_e32 v55, v0
	v_mov_b32_e32 v8, v0
	v_mov_b32_e32 v9, v0
	v_mov_b32_e32 v10, v0
	v_mov_b32_e32 v11, v0
	v_mov_b32_e32 v12, v0
	v_mov_b32_e32 v13, v0
	v_mov_b32_e32 v14, v0
	v_mov_b32_e32 v15, v0
	v_mov_b32_e32 v24, v0
	v_mov_b32_e32 v25, v0
	v_mov_b32_e32 v26, v0
	v_mov_b32_e32 v27, v0
	v_mov_b32_e32 v28, v0
	v_mov_b32_e32 v29, v0
	v_mov_b32_e32 v30, v0
	v_mov_b32_e32 v31, v0
	v_mov_b32_e32 v40, v0
	v_mov_b32_e32 v41, v0
	v_mov_b32_e32 v42, v0
	v_mov_b32_e32 v43, v0
	v_mov_b32_e32 v44, v0
	v_mov_b32_e32 v45, v0
	v_mov_b32_e32 v46, v0
	v_mov_b32_e32 v47, v0
	v_mov_b32_e32 v56, v0
	v_mov_b32_e32 v57, v0
	v_mov_b32_e32 v58, v0
	v_mov_b32_e32 v59, v0
	v_mov_b32_e32 v60, v0
	v_mov_b32_e32 v61, v0
	v_mov_b32_e32 v62, v0
	v_mov_b32_e32 v63, v0
	v_mov_b32_e32 v64, v0
	v_mov_b32_e32 v65, v0
	v_mov_b32_e32 v66, v0
	v_mov_b32_e32 v67, v0
	v_mov_b32_e32 v68, v0
	v_mov_b32_e32 v69, v0
	v_mov_b32_e32 v70, v0
	v_mov_b32_e32 v71, v0
	v_mov_b32_e32 v80, v0
	v_mov_b32_e32 v81, v0
	v_mov_b32_e32 v82, v0
	v_mov_b32_e32 v83, v0
	v_mov_b32_e32 v84, v0
	v_mov_b32_e32 v85, v0
	v_mov_b32_e32 v86, v0
	v_mov_b32_e32 v87, v0
	v_mov_b32_e32 v96, v0
	v_mov_b32_e32 v97, v0
	v_mov_b32_e32 v98, v0
	v_mov_b32_e32 v99, v0
	v_mov_b32_e32 v100, v0
	v_mov_b32_e32 v101, v0
	v_mov_b32_e32 v102, v0
	v_mov_b32_e32 v103, v0
	v_mov_b32_e32 v112, v0
	v_mov_b32_e32 v113, v0
	v_mov_b32_e32 v114, v0
	v_mov_b32_e32 v115, v0
	v_mov_b32_e32 v116, v0
	v_mov_b32_e32 v117, v0
	v_mov_b32_e32 v118, v0
	v_mov_b32_e32 v119, v0
	v_mov_b32_e32 v72, v0
	v_mov_b32_e32 v73, v0
	v_mov_b32_e32 v74, v0
	v_mov_b32_e32 v75, v0
	v_mov_b32_e32 v76, v0
	v_mov_b32_e32 v77, v0
	v_mov_b32_e32 v78, v0
	v_mov_b32_e32 v79, v0
	v_mov_b32_e32 v88, v0
	v_mov_b32_e32 v89, v0
	v_mov_b32_e32 v90, v0
	v_mov_b32_e32 v91, v0
	v_mov_b32_e32 v92, v0
	v_mov_b32_e32 v93, v0
	v_mov_b32_e32 v94, v0
	v_mov_b32_e32 v95, v0
	v_mov_b32_e32 v104, v0
	v_mov_b32_e32 v105, v0
	v_mov_b32_e32 v106, v0
	v_mov_b32_e32 v107, v0
	v_mov_b32_e32 v108, v0
	v_mov_b32_e32 v109, v0
	v_mov_b32_e32 v110, v0
	v_mov_b32_e32 v111, v0
	v_mov_b32_e32 v120, v0
	v_mov_b32_e32 v121, v0
	v_mov_b32_e32 v122, v0
	v_mov_b32_e32 v123, v0
	v_mov_b32_e32 v124, v0
	v_mov_b32_e32 v125, v0
	v_mov_b32_e32 v126, v0
	v_mov_b32_e32 v127, v0
	s_cmp_eq_u32 s97, 0
	s_cbranch_scc1 .LBB0_1543
	ds_read_b128 v[128:131], v167
	ds_read_b128 v[154:157], v167 offset:1024
	ds_read_b128 v[172:175], v167 offset:2048
	ds_read_b128 v[176:179], v167 offset:3072
	ds_read_b128 v[180:183], v168
	ds_read_b128 v[184:187], v168 offset:1024
	ds_read_b128 v[188:191], v168 offset:2048
	ds_read_b128 v[192:195], v168 offset:3072
	s_add_u32 s22, s20, 0x1000
	s_addc_u32 s23, s21, 0
	s_cmp_eq_u32 s54, 60
	s_cselect_b32 s27, s13, s23
	s_cselect_b32 s26, s50, s22
	s_cselect_b32 s25, s11, s53
	s_cselect_b32 s24, s51, s52
	v_lshl_add_u64 v[160:161], s[20:21], 0, v[144:145]
	s_add_i32 m0, s19, 0xc000
	s_nop 0
	global_load_lds_dwordx4 v[160:161], off
	v_lshl_add_u64 v[160:161], s[20:21], 0, v[146:147]
	s_add_i32 m0, s19, 0xe000
	s_nop 0
	global_load_lds_dwordx4 v[160:161], off
	ds_read_b128 v[196:199], v169
	ds_read_b128 v[200:203], v169 offset:1024
	ds_read_b128 v[204:207], v169 offset:2048
	ds_read_b128 v[208:211], v169 offset:3072
	ds_read_b128 v[212:215], v169 offset:4096
	ds_read_b128 v[216:219], v169 offset:5120
	ds_read_b128 v[220:223], v169 offset:6144
	ds_read_b128 v[224:227], v169 offset:7168
	s_waitcnt vmcnt(24)
	s_waitcnt lgkmcnt(0)
	s_barrier
	v_mfma_f32_16x16x32_bf16 v[124:127], v[128:131], v[196:199], v[124:127]
	v_mfma_f32_16x16x32_bf16 v[124:127], v[154:157], v[200:203], v[124:127]
	v_mfma_f32_16x16x32_bf16 v[120:123], v[176:179], v[200:203], v[120:123]
	v_mfma_f32_16x16x32_bf16 v[120:123], v[172:175], v[196:199], v[120:123]
	v_mfma_f32_16x16x32_bf16 v[116:119], v[180:183], v[196:199], v[116:119]
	v_mfma_f32_16x16x32_bf16 v[116:119], v[184:187], v[200:203], v[116:119]
	v_mfma_f32_16x16x32_bf16 v[112:115], v[192:195], v[200:203], v[112:115]
	v_mfma_f32_16x16x32_bf16 v[112:115], v[188:191], v[196:199], v[112:115]
	v_mfma_f32_16x16x32_bf16 v[96:99], v[188:191], v[204:207], v[96:99]
	v_mfma_f32_16x16x32_bf16 v[96:99], v[192:195], v[208:211], v[96:99]
	v_mfma_f32_16x16x32_bf16 v[100:103], v[184:187], v[208:211], v[100:103]
	v_mfma_f32_16x16x32_bf16 v[100:103], v[180:183], v[204:207], v[100:103]
	v_mfma_f32_16x16x32_bf16 v[104:107], v[172:175], v[204:207], v[104:107]
	v_mfma_f32_16x16x32_bf16 v[104:107], v[176:179], v[208:211], v[104:107]
	v_mfma_f32_16x16x32_bf16 v[108:111], v[154:157], v[208:211], v[108:111]
	v_mfma_f32_16x16x32_bf16 v[108:111], v[128:131], v[204:207], v[108:111]
	v_mfma_f32_16x16x32_bf16 v[92:95], v[128:131], v[212:215], v[92:95]
	v_mfma_f32_16x16x32_bf16 v[92:95], v[154:157], v[216:219], v[92:95]
	v_mfma_f32_16x16x32_bf16 v[88:91], v[176:179], v[216:219], v[88:91]
	v_mfma_f32_16x16x32_bf16 v[88:91], v[172:175], v[212:215], v[88:91]
	v_mfma_f32_16x16x32_bf16 v[84:87], v[180:183], v[212:215], v[84:87]
	v_mfma_f32_16x16x32_bf16 v[84:87], v[184:187], v[216:219], v[84:87]
	v_mfma_f32_16x16x32_bf16 v[80:83], v[192:195], v[216:219], v[80:83]
	v_mfma_f32_16x16x32_bf16 v[80:83], v[188:191], v[212:215], v[80:83]
	v_mfma_f32_16x16x32_bf16 v[64:67], v[188:191], v[220:223], v[64:67]
	v_mfma_f32_16x16x32_bf16 v[64:67], v[192:195], v[224:227], v[64:67]
	v_mfma_f32_16x16x32_bf16 v[68:71], v[184:187], v[224:227], v[68:71]
	v_mfma_f32_16x16x32_bf16 v[68:71], v[180:183], v[220:223], v[68:71]
	v_mfma_f32_16x16x32_bf16 v[72:75], v[172:175], v[220:223], v[72:75]
	v_mfma_f32_16x16x32_bf16 v[72:75], v[176:179], v[224:227], v[72:75]
	v_mfma_f32_16x16x32_bf16 v[76:79], v[154:157], v[224:227], v[76:79]
	v_mfma_f32_16x16x32_bf16 v[76:79], v[128:131], v[220:223], v[76:79]
	s_barrier
	s_add_i32 s20, s45, s30
	v_lshl_add_u64 v[160:161], s[24:25], 0, v[134:135]
	s_mov_b32 m0, s20
	v_lshl_add_u64 v[164:165], s[24:25], 0, v[138:139]
	global_load_lds_dwordx4 v[160:161], off
	s_add_i32 m0, s20, 0x2000
	s_add_u32 s20, s24, 0x100000
	s_addc_u32 s21, s25, 0
	s_add_i32 s55, s46, s30
	global_load_lds_dwordx4 v[164:165], off
	v_lshl_add_u64 v[196:197], s[20:21], 0, v[134:135]
	s_mov_b32 m0, s55
	v_lshl_add_u64 v[228:229], s[26:27], 0, v[132:133]
	global_load_lds_dwordx4 v[196:197], off
	v_lshl_add_u64 v[196:197], s[20:21], 0, v[138:139]
	s_add_i32 m0, s55, 0x2000
	v_lshl_add_u64 v[230:231], s[26:27], 0, v[136:137]
	global_load_lds_dwordx4 v[196:197], off
	s_mov_b32 m0, s19
	s_nop 0
	global_load_lds_dwordx4 v[228:229], off
	s_mov_b32 m0, s36
	s_nop 0
	global_load_lds_dwordx4 v[230:231], off
	ds_read_b128 v[196:199], v169 offset:16384
	ds_read_b128 v[200:203], v169 offset:17408
	ds_read_b128 v[204:207], v169 offset:18432
	ds_read_b128 v[208:211], v169 offset:19456
	ds_read_b128 v[212:215], v169 offset:20480
	ds_read_b128 v[216:219], v169 offset:21504
	ds_read_b128 v[220:223], v169 offset:22528
	ds_read_b128 v[224:227], v169 offset:23552
	s_waitcnt vmcnt(24)
	s_waitcnt lgkmcnt(0)
	s_barrier
	v_mfma_f32_16x16x32_bf16 v[60:63], v[128:131], v[196:199], v[60:63]
	v_mfma_f32_16x16x32_bf16 v[60:63], v[154:157], v[200:203], v[60:63]
	v_mfma_f32_16x16x32_bf16 v[56:59], v[176:179], v[200:203], v[56:59]
	v_mfma_f32_16x16x32_bf16 v[56:59], v[172:175], v[196:199], v[56:59]
	v_mfma_f32_16x16x32_bf16 v[52:55], v[180:183], v[196:199], v[52:55]
	v_mfma_f32_16x16x32_bf16 v[52:55], v[184:187], v[200:203], v[52:55]
	v_mfma_f32_16x16x32_bf16 v[48:51], v[192:195], v[200:203], v[48:51]
	v_mfma_f32_16x16x32_bf16 v[48:51], v[188:191], v[196:199], v[48:51]
	v_mfma_f32_16x16x32_bf16 v[32:35], v[188:191], v[204:207], v[32:35]
	v_mfma_f32_16x16x32_bf16 v[32:35], v[192:195], v[208:211], v[32:35]
	v_mfma_f32_16x16x32_bf16 v[36:39], v[184:187], v[208:211], v[36:39]
	v_mfma_f32_16x16x32_bf16 v[36:39], v[180:183], v[204:207], v[36:39]
	v_mfma_f32_16x16x32_bf16 v[40:43], v[172:175], v[204:207], v[40:43]
	v_mfma_f32_16x16x32_bf16 v[40:43], v[176:179], v[208:211], v[40:43]
	v_mfma_f32_16x16x32_bf16 v[44:47], v[154:157], v[208:211], v[44:47]
	v_mfma_f32_16x16x32_bf16 v[44:47], v[128:131], v[204:207], v[44:47]
	v_mfma_f32_16x16x32_bf16 v[28:31], v[128:131], v[212:215], v[28:31]
	v_mfma_f32_16x16x32_bf16 v[28:31], v[154:157], v[216:219], v[28:31]
	v_mfma_f32_16x16x32_bf16 v[24:27], v[176:179], v[216:219], v[24:27]
	v_mfma_f32_16x16x32_bf16 v[24:27], v[172:175], v[212:215], v[24:27]
	v_mfma_f32_16x16x32_bf16 v[20:23], v[180:183], v[212:215], v[20:23]
	v_mfma_f32_16x16x32_bf16 v[20:23], v[184:187], v[216:219], v[20:23]
	v_mfma_f32_16x16x32_bf16 v[16:19], v[192:195], v[216:219], v[16:19]
	v_mfma_f32_16x16x32_bf16 v[16:19], v[188:191], v[212:215], v[16:19]
	v_mfma_f32_16x16x32_bf16 v[0:3], v[188:191], v[220:223], v[0:3]
	v_mfma_f32_16x16x32_bf16 v[0:3], v[192:195], v[224:227], v[0:3]
	v_mfma_f32_16x16x32_bf16 v[4:7], v[184:187], v[224:227], v[4:7]
	v_mfma_f32_16x16x32_bf16 v[4:7], v[180:183], v[220:223], v[4:7]
	v_mfma_f32_16x16x32_bf16 v[8:11], v[172:175], v[220:223], v[8:11]
	v_mfma_f32_16x16x32_bf16 v[8:11], v[176:179], v[224:227], v[8:11]
	v_mfma_f32_16x16x32_bf16 v[12:15], v[154:157], v[224:227], v[12:15]
	v_mfma_f32_16x16x32_bf16 v[12:15], v[128:131], v[220:223], v[12:15]
	s_barrier
	s_add_i32 s55, 0, 0x18000
	v_add_u32_e32 v153, s55, v159
	s_add_i32 s56, 0, 0x1c000
	ds_read_b128 v[128:131], v153
	ds_read_b128 v[154:157], v153 offset:1024
	ds_read_b128 v[172:175], v153 offset:2048
	ds_read_b128 v[176:179], v153 offset:3072
	v_add_u32_e32 v153, s56, v159
	ds_read_b128 v[180:183], v153
	ds_read_b128 v[184:187], v153 offset:1024
	ds_read_b128 v[188:191], v153 offset:2048
	ds_read_b128 v[192:195], v153 offset:3072
	s_add_u32 s20, s26, 0x100000
	s_addc_u32 s21, s27, 0
	s_mov_b32 m0, s37
	v_lshl_add_u64 v[196:197], s[20:21], 0, v[132:133]
	global_load_lds_dwordx4 v[196:197], off
	v_lshl_add_u64 v[196:197], s[20:21], 0, v[136:137]
	s_mov_b32 m0, s38
	s_nop 0
	global_load_lds_dwordx4 v[196:197], off
	ds_read_b128 v[196:199], v169 offset:32768
	ds_read_b128 v[200:203], v169 offset:33792
	ds_read_b128 v[204:207], v169 offset:34816
	ds_read_b128 v[208:211], v169 offset:35840
	ds_read_b128 v[212:215], v169 offset:36864
	ds_read_b128 v[216:219], v169 offset:37888
	ds_read_b128 v[220:223], v169 offset:38912
	ds_read_b128 v[224:227], v169 offset:39936
	s_waitcnt vmcnt(8)
	s_waitcnt lgkmcnt(0)
	s_barrier
	v_mfma_f32_16x16x32_bf16 v[124:127], v[128:131], v[196:199], v[124:127]
	v_mfma_f32_16x16x32_bf16 v[124:127], v[154:157], v[200:203], v[124:127]
	v_mfma_f32_16x16x32_bf16 v[120:123], v[176:179], v[200:203], v[120:123]
	v_mfma_f32_16x16x32_bf16 v[120:123], v[172:175], v[196:199], v[120:123]
	v_mfma_f32_16x16x32_bf16 v[116:119], v[180:183], v[196:199], v[116:119]
	v_mfma_f32_16x16x32_bf16 v[116:119], v[184:187], v[200:203], v[116:119]
	v_mfma_f32_16x16x32_bf16 v[112:115], v[192:195], v[200:203], v[112:115]
	v_mfma_f32_16x16x32_bf16 v[112:115], v[188:191], v[196:199], v[112:115]
	v_mfma_f32_16x16x32_bf16 v[96:99], v[188:191], v[204:207], v[96:99]
	v_mfma_f32_16x16x32_bf16 v[96:99], v[192:195], v[208:211], v[96:99]
	v_mfma_f32_16x16x32_bf16 v[100:103], v[184:187], v[208:211], v[100:103]
	v_mfma_f32_16x16x32_bf16 v[100:103], v[180:183], v[204:207], v[100:103]
	v_mfma_f32_16x16x32_bf16 v[104:107], v[172:175], v[204:207], v[104:107]
	v_mfma_f32_16x16x32_bf16 v[104:107], v[176:179], v[208:211], v[104:107]
	v_mfma_f32_16x16x32_bf16 v[108:111], v[154:157], v[208:211], v[108:111]
	v_mfma_f32_16x16x32_bf16 v[108:111], v[128:131], v[204:207], v[108:111]
	v_mfma_f32_16x16x32_bf16 v[92:95], v[128:131], v[212:215], v[92:95]
	v_mfma_f32_16x16x32_bf16 v[92:95], v[154:157], v[216:219], v[92:95]
	v_mfma_f32_16x16x32_bf16 v[88:91], v[176:179], v[216:219], v[88:91]
	v_mfma_f32_16x16x32_bf16 v[88:91], v[172:175], v[212:215], v[88:91]
	v_mfma_f32_16x16x32_bf16 v[84:87], v[180:183], v[212:215], v[84:87]
	v_mfma_f32_16x16x32_bf16 v[84:87], v[184:187], v[216:219], v[84:87]
	v_mfma_f32_16x16x32_bf16 v[80:83], v[192:195], v[216:219], v[80:83]
	v_mfma_f32_16x16x32_bf16 v[80:83], v[188:191], v[212:215], v[80:83]
	v_mfma_f32_16x16x32_bf16 v[64:67], v[188:191], v[220:223], v[64:67]
	v_mfma_f32_16x16x32_bf16 v[64:67], v[192:195], v[224:227], v[64:67]
	v_mfma_f32_16x16x32_bf16 v[68:71], v[184:187], v[224:227], v[68:71]
	v_mfma_f32_16x16x32_bf16 v[68:71], v[180:183], v[220:223], v[68:71]
	v_mfma_f32_16x16x32_bf16 v[72:75], v[172:175], v[220:223], v[72:75]
	v_mfma_f32_16x16x32_bf16 v[72:75], v[176:179], v[224:227], v[72:75]
	v_mfma_f32_16x16x32_bf16 v[76:79], v[154:157], v[224:227], v[76:79]
	v_mfma_f32_16x16x32_bf16 v[76:79], v[128:131], v[220:223], v[76:79]
	s_barrier
	s_add_i32 s20, s55, s30
	v_lshl_add_u64 v[160:161], v[160:161], 0, s[8:9]
	s_mov_b32 m0, s20
	s_nop 0
	global_load_lds_dwordx4 v[160:161], off
	s_add_i32 m0, s20, 0x2000
	s_add_u32 s20, s24, 0x100800
	v_lshl_add_u64 v[160:161], v[164:165], 0, s[8:9]
	s_addc_u32 s21, s25, 0
	s_add_i32 s24, s56, s30
	global_load_lds_dwordx4 v[160:161], off
	v_lshl_add_u64 v[160:161], s[20:21], 0, v[134:135]
	s_mov_b32 m0, s24
	s_nop 0
	global_load_lds_dwordx4 v[160:161], off
	v_lshl_add_u64 v[160:161], s[20:21], 0, v[138:139]
	s_add_i32 m0, s24, 0x2000
	s_nop 0
	global_load_lds_dwordx4 v[160:161], off
	v_lshl_add_u64 v[160:161], v[228:229], 0, s[8:9]
	s_mov_b32 m0, s41
	s_nop 0
	global_load_lds_dwordx4 v[160:161], off
	v_lshl_add_u64 v[160:161], v[230:231], 0, s[8:9]
	s_mov_b32 m0, s42
	s_nop 0
	global_load_lds_dwordx4 v[160:161], off
	ds_read_b128 v[196:199], v169 offset:49152
	ds_read_b128 v[200:203], v169 offset:50176
	ds_read_b128 v[204:207], v169 offset:51200
	ds_read_b128 v[208:211], v169 offset:52224
	ds_read_b128 v[212:215], v169 offset:53248
	ds_read_b128 v[216:219], v169 offset:54272
	ds_read_b128 v[220:223], v169 offset:55296
	ds_read_b128 v[224:227], v169 offset:56320
	s_waitcnt vmcnt(8)
	s_waitcnt lgkmcnt(0)
	s_barrier
	v_mfma_f32_16x16x32_bf16 v[60:63], v[128:131], v[196:199], v[60:63]
	v_mfma_f32_16x16x32_bf16 v[60:63], v[154:157], v[200:203], v[60:63]
	v_mfma_f32_16x16x32_bf16 v[56:59], v[176:179], v[200:203], v[56:59]
	v_mfma_f32_16x16x32_bf16 v[56:59], v[172:175], v[196:199], v[56:59]
	v_mfma_f32_16x16x32_bf16 v[52:55], v[180:183], v[196:199], v[52:55]
	v_mfma_f32_16x16x32_bf16 v[52:55], v[184:187], v[200:203], v[52:55]
	v_mfma_f32_16x16x32_bf16 v[48:51], v[192:195], v[200:203], v[48:51]
	v_mfma_f32_16x16x32_bf16 v[48:51], v[188:191], v[196:199], v[48:51]
	v_mfma_f32_16x16x32_bf16 v[32:35], v[188:191], v[204:207], v[32:35]
	v_mfma_f32_16x16x32_bf16 v[32:35], v[192:195], v[208:211], v[32:35]
	v_mfma_f32_16x16x32_bf16 v[36:39], v[184:187], v[208:211], v[36:39]
	v_mfma_f32_16x16x32_bf16 v[36:39], v[180:183], v[204:207], v[36:39]
	v_mfma_f32_16x16x32_bf16 v[40:43], v[172:175], v[204:207], v[40:43]
	v_mfma_f32_16x16x32_bf16 v[40:43], v[176:179], v[208:211], v[40:43]
	v_mfma_f32_16x16x32_bf16 v[44:47], v[154:157], v[208:211], v[44:47]
	v_mfma_f32_16x16x32_bf16 v[44:47], v[128:131], v[204:207], v[44:47]
	v_mfma_f32_16x16x32_bf16 v[28:31], v[128:131], v[212:215], v[28:31]
	v_mfma_f32_16x16x32_bf16 v[28:31], v[154:157], v[216:219], v[28:31]
	v_mfma_f32_16x16x32_bf16 v[24:27], v[176:179], v[216:219], v[24:27]
	v_mfma_f32_16x16x32_bf16 v[24:27], v[172:175], v[212:215], v[24:27]
	v_mfma_f32_16x16x32_bf16 v[20:23], v[180:183], v[212:215], v[20:23]
	v_mfma_f32_16x16x32_bf16 v[20:23], v[184:187], v[216:219], v[20:23]
	v_mfma_f32_16x16x32_bf16 v[16:19], v[192:195], v[216:219], v[16:19]
	v_mfma_f32_16x16x32_bf16 v[16:19], v[188:191], v[212:215], v[16:19]
	v_mfma_f32_16x16x32_bf16 v[0:3], v[188:191], v[220:223], v[0:3]
	v_mfma_f32_16x16x32_bf16 v[0:3], v[192:195], v[224:227], v[0:3]
	v_mfma_f32_16x16x32_bf16 v[4:7], v[184:187], v[224:227], v[4:7]
	v_mfma_f32_16x16x32_bf16 v[4:7], v[180:183], v[220:223], v[4:7]
	v_mfma_f32_16x16x32_bf16 v[8:11], v[172:175], v[220:223], v[8:11]
	v_mfma_f32_16x16x32_bf16 v[8:11], v[176:179], v[224:227], v[8:11]
	v_mfma_f32_16x16x32_bf16 v[12:15], v[154:157], v[224:227], v[12:15]
	v_mfma_f32_16x16x32_bf16 v[12:15], v[128:131], v[220:223], v[12:15]
	s_barrier
	s_add_i32 s54, s54, 2
	s_add_u32 s52, s52, 0x1000
	s_addc_u32 s53, s53, 0
	s_cmp_gt_u32 s54, 61
	s_mov_b64 s[20:21], s[22:23]
	s_cbranch_scc1 .Lpeel_exit_P8

.Lpeel_exit_P8:
.LBB0_1546:
	s_cmp_eq_u32 s18, s28
	s_mov_b64 s[20:21], -1
	s_cbranch_scc1 .LBB0_1548
	v_lshl_or_b32 v154, s18, 8, v166
	v_ashrrev_i32_e32 v155, 31, v154
	v_lshlrev_b64 v[128:129], 8, v[154:155]
	v_lshl_add_u64 v[128:129], v[142:143], 0, v[128:129]
	global_load_dwordx4 v[172:175], v[128:129], off
	global_load_dwordx4 v[176:179], v[128:129], off offset:16
	global_load_dwordx4 v[180:183], v[128:129], off offset:32
	s_nop 0
	global_load_dwordx4 v[128:131], v[128:129], off offset:48
	v_or_b32_e32 v156, 16, v154
	v_ashrrev_i32_e32 v157, 31, v156
	v_lshlrev_b64 v[156:157], 8, v[156:157]
	v_lshl_add_u64 v[156:157], v[142:143], 0, v[156:157]
	global_load_dwordx4 v[184:187], v[156:157], off
	global_load_dwordx4 v[188:191], v[156:157], off offset:16
	global_load_dwordx4 v[192:195], v[156:157], off offset:48
	global_load_dwordx4 v[196:199], v[156:157], off offset:32
	v_or_b32_e32 v156, 32, v154
	v_ashrrev_i32_e32 v157, 31, v156
	v_lshlrev_b64 v[156:157], 8, v[156:157]
	v_lshl_add_u64 v[156:157], v[142:143], 0, v[156:157]
	global_load_dwordx4 v[200:203], v[156:157], off
	global_load_dwordx4 v[204:207], v[156:157], off offset:16
	global_load_dwordx4 v[208:211], v[156:157], off offset:48
	global_load_dwordx4 v[212:215], v[156:157], off offset:32
	v_or_b32_e32 v160, 48, v154
	v_ashrrev_i32_e32 v161, 31, v160
	v_lshlrev_b64 v[156:157], 8, v[160:161]
	v_lshl_add_u64 v[156:157], v[142:143], 0, v[156:157]
	global_load_dwordx4 v[216:219], v[156:157], off offset:48
	global_load_dwordx4 v[220:223], v[156:157], off offset:32
	global_load_dwordx4 v[224:227], v[156:157], off offset:16
	global_load_dwordx4 v[228:231], v[156:157], off
	v_or_b32_e32 v164, 0x80, v154
	v_ashrrev_i32_e32 v165, 31, v164
	v_lshlrev_b64 v[160:161], 8, v[164:165]
	v_and_b32_e32 v155, 64, v171
	v_xor_b32_e32 v153, 16, v171
	v_add_u32_e32 v155, 64, v155
	v_xor_b32_e32 v158, 32, v171
	v_cmp_lt_i32_e32 vcc, v153, v155
	v_lshl_add_u64 v[160:161], v[142:143], 0, v[160:161]
	global_load_dwordx4 v[232:235], v[160:161], off offset:16
	global_load_dwordx4 v[236:239], v[160:161], off
	v_cndmask_b32_e32 v153, v171, v153, vcc
	v_cmp_lt_i32_e32 vcc, v158, v155
	v_lshlrev_b32_e32 v153, 2, v153
	s_nop 0
	v_cndmask_b32_e32 v155, v171, v158, vcc
	v_lshlrev_b32_e32 v240, 2, v155
	s_waitcnt vmcnt(0)
	v_mov_b32_e32 v156, v173
	v_mov_b32_e32 v157, v174
	v_mov_b32_e32 v173, v175
	v_mov_b32_e32 v164, v177
	v_mov_b32_e32 v165, v178
	v_mov_b32_e32 v177, v179
	v_mov_b32_e32 v175, v130
	v_mov_b32_e32 v179, v131
	v_pk_add_f32 v[130:131], v[156:157], v[172:173]
	v_pk_add_f32 v[156:157], v[164:165], v[176:177]
	v_add_f32_e32 v174, v180, v181
	v_mov_b32_e32 v181, v128
	v_add_f32_e32 v128, v130, v131
	v_pk_add_f32 v[130:131], v[156:157], v[156:157] op_sel:[0,1] op_sel_hi:[1,0]
	v_add_f32_e32 v178, v182, v183
	v_add_f32_e32 v180, 0, v128
	v_mov_b32_e32 v131, v129
	v_pk_add_f32 v[164:165], v[174:175], v[178:179]
	v_pk_add_f32 v[130:131], v[180:181], v[130:131]
	v_mov_b32_e32 v172, v185
	v_mov_b32_e32 v173, v186
	v_mov_b32_e32 v185, v187
	v_mov_b32_e32 v174, v189
	v_mov_b32_e32 v175, v190
	v_mov_b32_e32 v189, v191
	v_pk_add_f32 v[130:131], v[130:131], v[164:165]
	v_pk_add_f32 v[156:157], v[172:173], v[184:185]
	v_pk_add_f32 v[172:173], v[174:175], v[188:189]
	v_add_f32_e32 v130, v130, v131
	v_add_f32_e32 v155, v156, v157
	v_pk_add_f32 v[128:129], v[172:173], v[172:173] op_sel:[0,1] op_sel_hi:[1,0]
	ds_bpermute_b32 v131, v153, v130
	v_add_f32_e32 v176, v196, v197
	v_add_f32_e32 v178, v198, v199
	v_mov_b32_e32 v183, v192
	v_mov_b32_e32 v177, v194
	v_mov_b32_e32 v179, v195
	v_add_f32_e32 v182, 0, v155
	v_mov_b32_e32 v129, v193
	v_pk_add_f32 v[174:175], v[176:177], v[178:179]
	v_pk_add_f32 v[128:129], v[182:183], v[128:129]
	s_waitcnt lgkmcnt(0)
	v_add_f32_e32 v130, v130, v131
	v_pk_add_f32 v[128:129], v[128:129], v[174:175]
	ds_bpermute_b32 v131, v240, v130
	v_add_f32_e32 v155, v128, v129
	ds_bpermute_b32 v156, v153, v155
	v_mov_b32_e32 v186, v201
	v_mov_b32_e32 v187, v202
	v_mov_b32_e32 v201, v203
	v_pk_add_f32 v[128:129], v[186:187], v[200:201]
	s_waitcnt lgkmcnt(0)
	v_add_f32_e32 v155, v155, v156
	v_add_f32_e32 v128, v128, v129
	v_add_f32_e32 v156, 0, v128
	v_mov_b32_e32 v128, v205
	v_mov_b32_e32 v129, v206
	v_mov_b32_e32 v205, v207
	v_add_f32_e32 v162, v130, v131
	v_pk_add_f32 v[164:165], v[128:129], v[204:205]
	global_load_dwordx4 v[128:131], v[160:161], off offset:48
	global_load_dwordx4 v[172:175], v[160:161], off offset:32
	v_pk_add_f32 v[160:161], v[164:165], v[164:165] op_sel:[0,1] op_sel_hi:[1,0]
	v_add_f32_e32 v164, v212, v213
	v_add_f32_e32 v176, v214, v215
	v_mov_b32_e32 v157, v208
	v_mov_b32_e32 v161, v209
	v_mov_b32_e32 v165, v210
	v_mov_b32_e32 v177, v211
	v_pk_add_f32 v[156:157], v[156:157], v[160:161]
	v_pk_add_f32 v[160:161], v[164:165], v[176:177]
	ds_bpermute_b32 v158, v240, v155
	v_pk_add_f32 v[156:157], v[156:157], v[160:161]
	v_or_b32_e32 v192, 0xa0, v154
	v_add_f32_e32 v160, v156, v157
	v_or_b32_e32 v156, 0x90, v154
	v_ashrrev_i32_e32 v157, 31, v156
	v_lshlrev_b64 v[156:157], 8, v[156:157]
	v_lshl_add_u64 v[156:157], v[142:143], 0, v[156:157]
	global_load_dwordx4 v[176:179], v[156:157], off offset:16
	global_load_dwordx4 v[180:183], v[156:157], off
	global_load_dwordx4 v[184:187], v[156:157], off offset:48
	global_load_dwordx4 v[188:191], v[156:157], off offset:32
	ds_bpermute_b32 v161, v153, v160
	v_ashrrev_i32_e32 v193, 31, v192
	s_waitcnt lgkmcnt(1)
	v_add_f32_e32 v155, v155, v158
	v_lshlrev_b64 v[192:193], 8, v[192:193]
	v_lshl_add_u64 v[204:205], v[142:143], 0, v[192:193]
	s_waitcnt lgkmcnt(0)
	v_add_f32_e32 v158, v160, v161
	v_mov_b32_e32 v160, v229
	v_mov_b32_e32 v161, v230
	v_mov_b32_e32 v229, v231
	v_pk_add_f32 v[156:157], v[160:161], v[228:229]
	v_mov_b32_e32 v160, v225
	v_mov_b32_e32 v161, v226
	v_mov_b32_e32 v225, v227
	v_pk_add_f32 v[160:161], v[160:161], v[224:225]
	global_load_dwordx4 v[192:195], v[204:205], off offset:16
	global_load_dwordx4 v[196:199], v[204:205], off
	v_add_f32_e32 v156, v156, v157
	v_pk_add_f32 v[160:161], v[160:161], v[160:161] op_sel:[0,1] op_sel_hi:[1,0]
	v_add_f32_e32 v156, 0, v156
	v_add_f32_e32 v200, v220, v221
	v_add_f32_e32 v202, v222, v223
	v_mov_b32_e32 v157, v216
	v_mov_b32_e32 v161, v217
	v_mov_b32_e32 v201, v218
	v_mov_b32_e32 v203, v219
	v_pk_add_f32 v[156:157], v[156:157], v[160:161]
	v_pk_add_f32 v[160:161], v[200:201], v[202:203]
	global_load_dwordx4 v[200:203], v[204:205], off offset:48
	s_nop 0
	global_load_dwordx4 v[204:207], v[204:205], off offset:32
	v_fmamk_f32 v162, v162, 0x39800000, v170
	v_fmamk_f32 v155, v155, 0x39800000, v170
	v_or_b32_e32 v154, 0xb0, v154
	v_rsq_f32_e32 v164, v162
	v_rsq_f32_e32 v162, v155
	v_ashrrev_i32_e32 v155, 31, v154
	v_lshlrev_b64 v[154:155], 8, v[154:155]
	v_lshl_add_u64 v[154:155], v[142:143], 0, v[154:155]
	global_load_dwordx4 v[208:211], v[154:155], off offset:16
	global_load_dwordx4 v[212:215], v[154:155], off
	global_load_dwordx4 v[216:219], v[154:155], off offset:48
	global_load_dwordx4 v[220:223], v[154:155], off offset:32
	v_pk_add_f32 v[156:157], v[156:157], v[160:161]
	ds_bpermute_b32 v165, v240, v158
	v_add_f32_e32 v156, v156, v157
	ds_bpermute_b32 v157, v153, v156
	v_mov_b32_e32 v154, v237
	v_mov_b32_e32 v155, v238
	s_waitcnt lgkmcnt(1)
	v_add_f32_e32 v158, v158, v165
	v_mov_b32_e32 v237, v239
	s_waitcnt lgkmcnt(0)
	v_add_f32_e32 v165, v156, v157
	v_mov_b32_e32 v156, v233
	v_mov_b32_e32 v157, v234
	v_mov_b32_e32 v233, v235
	v_pk_add_f32 v[154:155], v[154:155], v[236:237]
	v_pk_add_f32 v[156:157], v[156:157], v[232:233]
	v_add_f32_e32 v154, v154, v155
	v_pk_add_f32 v[156:157], v[156:157], v[156:157] op_sel:[0,1] op_sel_hi:[1,0]
	v_add_f32_e32 v154, 0, v154
	ds_bpermute_b32 v224, v240, v165
	s_waitcnt vmcnt(13)
	v_mov_b32_e32 v155, v128
	s_waitcnt vmcnt(12)
	v_add_f32_e32 v160, v172, v173
	v_add_f32_e32 v172, v174, v175
	v_mov_b32_e32 v157, v129
	v_mov_b32_e32 v161, v130
	v_mov_b32_e32 v173, v131
	v_pk_add_f32 v[128:129], v[154:155], v[156:157]
	v_pk_add_f32 v[130:131], v[160:161], v[172:173]
	s_waitcnt vmcnt(9)
	v_mov_b32_e32 v155, v186
	v_pk_add_f32 v[128:129], v[128:129], v[130:131]
	v_fmamk_f32 v130, v158, 0x39800000, v170
	v_add_f32_e32 v128, v128, v129
	ds_bpermute_b32 v129, v153, v128
	v_rsq_f32_e32 v160, v130
	s_waitcnt lgkmcnt(1)
	v_add_f32_e32 v130, v165, v224
	v_fmamk_f32 v158, v130, 0x39800000, v170
	v_mov_b32_e32 v130, v177
	s_waitcnt lgkmcnt(0)
	v_add_f32_e32 v161, v128, v129
	v_mov_b32_e32 v128, v181
	v_mov_b32_e32 v129, v182
	v_mov_b32_e32 v181, v183
	v_mov_b32_e32 v131, v178
	v_mov_b32_e32 v177, v179
	v_pk_add_f32 v[128:129], v[128:129], v[180:181]
	v_pk_add_f32 v[130:131], v[130:131], v[176:177]
	v_add_f32_e32 v128, v128, v129
	v_pk_add_f32 v[130:131], v[130:131], v[130:131] op_sel:[0,1] op_sel_hi:[1,0]
	v_add_f32_e32 v128, 0, v128
	s_waitcnt vmcnt(8)
	v_add_f32_e32 v154, v188, v189
	v_add_f32_e32 v156, v190, v191
	v_mov_b32_e32 v129, v184
	v_mov_b32_e32 v131, v185
	v_mov_b32_e32 v157, v187
	v_pk_add_f32 v[128:129], v[128:129], v[130:131]
	v_pk_add_f32 v[130:131], v[154:155], v[156:157]
	ds_bpermute_b32 v165, v240, v161
	v_pk_add_f32 v[128:129], v[128:129], v[130:131]
	s_waitcnt vmcnt(7)
	v_mov_b32_e32 v131, v194
	v_add_f32_e32 v128, v128, v129
	ds_bpermute_b32 v129, v153, v128
	s_waitcnt lgkmcnt(1)
	v_add_f32_e32 v130, v161, v165
	v_fmamk_f32 v130, v130, 0x39800000, v170
	v_rsq_f32_e32 v156, v130
	v_mov_b32_e32 v130, v193
	s_waitcnt lgkmcnt(0)
	v_add_f32_e32 v157, v128, v129
	s_waitcnt vmcnt(6)
	v_mov_b32_e32 v128, v197
	v_mov_b32_e32 v129, v198
	v_mov_b32_e32 v197, v199
	v_mov_b32_e32 v193, v195
	v_pk_add_f32 v[128:129], v[128:129], v[196:197]
	v_pk_add_f32 v[130:131], v[130:131], v[192:193]
	v_add_f32_e32 v128, v128, v129
	v_pk_add_f32 v[130:131], v[130:131], v[130:131] op_sel:[0,1] op_sel_hi:[1,0]
	v_add_f32_e32 v128, 0, v128
	s_waitcnt vmcnt(4)
	v_add_f32_e32 v154, v204, v205
	v_add_f32_e32 v172, v206, v207
	v_mov_b32_e32 v129, v200
	v_mov_b32_e32 v131, v201
	v_mov_b32_e32 v155, v202
	v_mov_b32_e32 v173, v203
	v_pk_add_f32 v[128:129], v[128:129], v[130:131]
	v_pk_add_f32 v[130:131], v[154:155], v[172:173]
	s_waitcnt vmcnt(0)
	v_add_f32_e32 v154, v220, v221
	v_pk_add_f32 v[128:129], v[128:129], v[130:131]
	v_mov_b32_e32 v130, v209
	v_add_f32_e32 v165, v128, v129
	v_mov_b32_e32 v128, v213
	v_mov_b32_e32 v129, v214
	v_mov_b32_e32 v213, v215
	v_mov_b32_e32 v131, v210
	v_mov_b32_e32 v209, v211
	v_pk_add_f32 v[128:129], v[128:129], v[212:213]
	v_pk_add_f32 v[130:131], v[130:131], v[208:209]
	v_add_f32_e32 v128, v128, v129
	v_pk_add_f32 v[130:131], v[130:131], v[130:131] op_sel:[0,1] op_sel_hi:[1,0]
	v_add_f32_e32 v128, 0, v128
	v_add_f32_e32 v172, v222, v223
	v_mov_b32_e32 v129, v216
	v_mov_b32_e32 v131, v217
	v_mov_b32_e32 v155, v218
	v_mov_b32_e32 v173, v219
	v_pk_add_f32 v[128:129], v[128:129], v[130:131]
	v_pk_add_f32 v[130:131], v[154:155], v[172:173]
	ds_bpermute_b32 v174, v153, v165
	v_pk_add_f32 v[128:129], v[128:129], v[130:131]
	ds_bpermute_b32 v161, v240, v157
	v_add_f32_e32 v128, v128, v129
	ds_bpermute_b32 v129, v153, v128
	s_waitcnt lgkmcnt(2)
	v_add_f32_e32 v131, v165, v174
	ds_bpermute_b32 v153, v240, v131
	s_waitcnt lgkmcnt(2)
	v_add_f32_e32 v130, v157, v161
	v_fmamk_f32 v130, v130, 0x39800000, v170
	s_waitcnt lgkmcnt(1)
	v_add_f32_e32 v128, v128, v129
	ds_bpermute_b32 v129, v240, v128
	v_rsq_f32_e32 v154, v130
	s_waitcnt lgkmcnt(1)
	v_add_f32_e32 v130, v131, v153
	v_fmamk_f32 v130, v130, 0x39800000, v170
	v_rsq_f32_e32 v158, v158
	s_waitcnt lgkmcnt(0)
	v_add_f32_e32 v128, v128, v129
	v_fmamk_f32 v128, v128, 0x39800000, v170
	v_rsq_f32_e32 v130, v130
	v_rsq_f32_e32 v128, v128
	s_cbranch_execz .LBB0_1549
	s_branch .LBB0_1550

.Lepibar_P8:
	s_mov_b32 s97, 1
	v_pk_mul_f32 v[86:87], v[86:87], v[160:161] op_sel_hi:[1,0]
	v_max_f32_e32 v84, 0, v84
	v_mul_f32_e32 v88, v80, v80
	v_max_f32_e32 v80, 0, v85
	v_max_f32_e32 v81, 0, v81
	v_max_f32_e32 v82, 0, v82
	s_add_u32 s22, s22, s20
	v_mul_f32_e32 v84, v84, v84
	v_mul_f32_e32 v80, v80, v80
	v_mul_f32_e32 v85, v81, v81
	v_max_f32_e32 v81, 0, v86
	v_mul_f32_e32 v86, v82, v82
	v_max_f32_e32 v82, 0, v87
	s_addc_u32 s23, 0, s21
	v_mul_f32_e32 v81, v81, v81
	v_mul_f32_e32 v82, v82, v82
	v_max_f32_e32 v83, 0, v83
	v_cvt_pk_bf16_f32 v80, v84, v80
	v_add_co_u32_e32 v84, vcc, s48, v96
	s_lshl_b64 s[22:23], s[22:23], 10
	v_pk_mul_f32 v[72:73], v[72:73], v[158:159] op_sel_hi:[1,0]
	v_mul_f32_e32 v83, v83, v83
	v_cvt_pk_bf16_f32 v81, v81, v82
	v_cvt_pk_bf16_f32 v82, v88, v85
	v_addc_co_u32_e32 v85, vcc, 0, v97, vcc
	s_add_u32 s22, s11, s22
	v_pk_mul_f32 v[76:77], v[76:77], v[158:159] op_sel_hi:[1,0]
	v_pk_mul_f32 v[74:75], v[74:75], v[158:159] op_sel_hi:[1,0]
	v_max_f32_e32 v72, 0, v72
	v_cvt_pk_bf16_f32 v83, v86, v83
	global_store_dwordx4 v[84:85], v[80:83], off
	s_addc_u32 s23, s13, s23
	v_pk_mul_f32 v[78:79], v[78:79], v[158:159] op_sel_hi:[1,0]
	v_mul_f32_e32 v82, v72, v72
	v_max_f32_e32 v72, 0, v77
	v_max_f32_e32 v73, 0, v73
	v_max_f32_e32 v74, 0, v74
	v_lshl_add_u64 v[80:81], s[22:23], 0, v[140:141]
	v_max_f32_e32 v76, 0, v76
	v_mul_f32_e32 v72, v72, v72
	v_mul_f32_e32 v77, v73, v73
	v_max_f32_e32 v73, 0, v78
	v_mul_f32_e32 v78, v74, v74
	v_max_f32_e32 v74, 0, v79
	v_max_f32_e32 v75, 0, v75
	v_pk_mul_f32 v[64:65], v[64:65], v[158:159] op_sel_hi:[1,0]
	v_lshl_add_u64 v[80:81], v[80:81], 0, v[152:153]
	v_mul_f32_e32 v76, v76, v76
	v_mul_f32_e32 v73, v73, v73
	v_mul_f32_e32 v74, v74, v74
	v_mul_f32_e32 v75, v75, v75
	v_cvt_pk_bf16_f32 v72, v76, v72
	v_pk_mul_f32 v[68:69], v[68:69], v[158:159] op_sel_hi:[1,0]
	v_pk_mul_f32 v[66:67], v[66:67], v[158:159] op_sel_hi:[1,0]
	v_max_f32_e32 v64, 0, v64
	s_or_b32 s22, s18, 0x1000
	v_cvt_pk_bf16_f32 v73, v73, v74
	v_cvt_pk_bf16_f32 v74, v82, v77
	v_cvt_pk_bf16_f32 v75, v78, v75
	global_store_dwordx4 v[80:81], v[72:75], off
	v_pk_mul_f32 v[70:71], v[70:71], v[158:159] op_sel_hi:[1,0]
	v_max_f32_e32 v68, 0, v68
	v_mul_f32_e32 v72, v64, v64
	v_max_f32_e32 v64, 0, v69
	v_max_f32_e32 v65, 0, v65
	v_max_f32_e32 v66, 0, v66
	s_add_u32 s22, s22, s20
	v_mul_f32_e32 v68, v68, v68
	v_mul_f32_e32 v64, v64, v64
	v_mul_f32_e32 v69, v65, v65
	v_max_f32_e32 v65, 0, v70
	v_mul_f32_e32 v70, v66, v66
	v_max_f32_e32 v66, 0, v71
	s_addc_u32 s23, 0, s21
	v_mul_f32_e32 v65, v65, v65
	v_mul_f32_e32 v66, v66, v66
	v_max_f32_e32 v67, 0, v67
	v_cvt_pk_bf16_f32 v64, v68, v64
	v_add_co_u32_e32 v68, vcc, s48, v80
	s_lshl_b64 s[22:23], s[22:23], 10
	v_pk_mul_f32 v[56:57], v[56:57], v[156:157] op_sel_hi:[1,0]
	v_mul_f32_e32 v67, v67, v67
	v_cvt_pk_bf16_f32 v65, v65, v66
	v_cvt_pk_bf16_f32 v66, v72, v69
	v_addc_co_u32_e32 v69, vcc, 0, v81, vcc
	s_add_u32 s22, s11, s22
	v_pk_mul_f32 v[60:61], v[60:61], v[156:157] op_sel_hi:[1,0]
	v_pk_mul_f32 v[58:59], v[58:59], v[156:157] op_sel_hi:[1,0]
	v_max_f32_e32 v56, 0, v56
	v_cvt_pk_bf16_f32 v67, v70, v67
	global_store_dwordx4 v[68:69], v[64:67], off
	s_addc_u32 s23, s13, s23
	v_pk_mul_f32 v[62:63], v[62:63], v[156:157] op_sel_hi:[1,0]
	v_mul_f32_e32 v66, v56, v56
	v_max_f32_e32 v56, 0, v61
	v_max_f32_e32 v57, 0, v57
	v_max_f32_e32 v58, 0, v58
	v_lshl_add_u64 v[64:65], s[22:23], 0, v[140:141]
	v_max_f32_e32 v60, 0, v60
	v_mul_f32_e32 v56, v56, v56
	v_mul_f32_e32 v61, v57, v57
	v_max_f32_e32 v57, 0, v62
	v_mul_f32_e32 v62, v58, v58
	v_max_f32_e32 v58, 0, v63
	v_max_f32_e32 v59, 0, v59
	v_pk_mul_f32 v[48:49], v[48:49], v[156:157] op_sel_hi:[1,0]
	v_lshl_add_u64 v[64:65], v[64:65], 0, v[152:153]
	v_mul_f32_e32 v60, v60, v60
	v_mul_f32_e32 v57, v57, v57
	v_mul_f32_e32 v58, v58, v58
	v_mul_f32_e32 v59, v59, v59
	v_cvt_pk_bf16_f32 v56, v60, v56
	v_pk_mul_f32 v[52:53], v[52:53], v[156:157] op_sel_hi:[1,0]
	v_pk_mul_f32 v[50:51], v[50:51], v[156:157] op_sel_hi:[1,0]
	v_max_f32_e32 v48, 0, v48
	s_or_b32 s22, s18, 0x1200
	v_cvt_pk_bf16_f32 v57, v57, v58
	v_cvt_pk_bf16_f32 v58, v66, v61
	v_cvt_pk_bf16_f32 v59, v62, v59
	global_store_dwordx4 v[64:65], v[56:59], off
	v_pk_mul_f32 v[54:55], v[54:55], v[156:157] op_sel_hi:[1,0]
	v_max_f32_e32 v52, 0, v52
	v_mul_f32_e32 v56, v48, v48
	v_max_f32_e32 v48, 0, v53
	v_max_f32_e32 v49, 0, v49
	v_max_f32_e32 v50, 0, v50
	s_add_u32 s22, s22, s20
	v_mul_f32_e32 v52, v52, v52
	v_mul_f32_e32 v48, v48, v48
	v_mul_f32_e32 v53, v49, v49
	v_max_f32_e32 v49, 0, v54
	v_mul_f32_e32 v54, v50, v50
	v_max_f32_e32 v50, 0, v55
	s_addc_u32 s23, 0, s21
	v_mul_f32_e32 v49, v49, v49
	v_mul_f32_e32 v50, v50, v50
	v_max_f32_e32 v51, 0, v51
	v_cvt_pk_bf16_f32 v48, v52, v48
	v_add_co_u32_e32 v52, vcc, s48, v64
	s_lshl_b64 s[22:23], s[22:23], 10
	v_pk_mul_f32 v[40:41], v[40:41], v[154:155] op_sel_hi:[1,0]
	v_mul_f32_e32 v51, v51, v51
	v_cvt_pk_bf16_f32 v49, v49, v50
	v_cvt_pk_bf16_f32 v50, v56, v53
	v_addc_co_u32_e32 v53, vcc, 0, v65, vcc
	s_add_u32 s22, s11, s22
	v_pk_mul_f32 v[44:45], v[44:45], v[154:155] op_sel_hi:[1,0]
	v_pk_mul_f32 v[42:43], v[42:43], v[154:155] op_sel_hi:[1,0]
	v_max_f32_e32 v40, 0, v40
	v_cvt_pk_bf16_f32 v51, v54, v51
	global_store_dwordx4 v[52:53], v[48:51], off
	s_addc_u32 s23, s13, s23
	v_pk_mul_f32 v[46:47], v[46:47], v[154:155] op_sel_hi:[1,0]
	v_mul_f32_e32 v50, v40, v40
	v_max_f32_e32 v40, 0, v45
	v_max_f32_e32 v41, 0, v41
	v_max_f32_e32 v42, 0, v42
	v_lshl_add_u64 v[48:49], s[22:23], 0, v[140:141]
	v_max_f32_e32 v44, 0, v44
	v_mul_f32_e32 v40, v40, v40
	v_mul_f32_e32 v45, v41, v41
	v_max_f32_e32 v41, 0, v46
	v_mul_f32_e32 v46, v42, v42
	v_max_f32_e32 v42, 0, v47
	v_max_f32_e32 v43, 0, v43
	v_pk_mul_f32 v[32:33], v[32:33], v[154:155] op_sel_hi:[1,0]
	v_lshl_add_u64 v[48:49], v[48:49], 0, v[152:153]
	v_mul_f32_e32 v44, v44, v44
	v_mul_f32_e32 v41, v41, v41
	v_mul_f32_e32 v42, v42, v42
	v_mul_f32_e32 v43, v43, v43
	v_cvt_pk_bf16_f32 v40, v44, v40
	v_pk_mul_f32 v[36:37], v[36:37], v[154:155] op_sel_hi:[1,0]
	v_pk_mul_f32 v[34:35], v[34:35], v[154:155] op_sel_hi:[1,0]
	v_max_f32_e32 v32, 0, v32
	s_or_b32 s22, s18, 0x1400
	v_cvt_pk_bf16_f32 v41, v41, v42
	v_cvt_pk_bf16_f32 v42, v50, v45
	v_cvt_pk_bf16_f32 v43, v46, v43
	global_store_dwordx4 v[48:49], v[40:43], off
	v_pk_mul_f32 v[38:39], v[38:39], v[154:155] op_sel_hi:[1,0]
	v_max_f32_e32 v36, 0, v36
	v_mul_f32_e32 v40, v32, v32
	v_max_f32_e32 v32, 0, v37
	v_max_f32_e32 v33, 0, v33
	v_max_f32_e32 v34, 0, v34
	s_add_u32 s22, s22, s20
	v_mul_f32_e32 v36, v36, v36
	v_mul_f32_e32 v32, v32, v32
	v_mul_f32_e32 v37, v33, v33
	v_max_f32_e32 v33, 0, v38
	v_mul_f32_e32 v38, v34, v34
	v_max_f32_e32 v34, 0, v39
	s_addc_u32 s23, 0, s21
	v_mul_f32_e32 v33, v33, v33
	v_mul_f32_e32 v34, v34, v34
	v_max_f32_e32 v35, 0, v35
	v_cvt_pk_bf16_f32 v32, v36, v32
	v_add_co_u32_e32 v36, vcc, s48, v48
	s_lshl_b64 s[22:23], s[22:23], 10
	v_pk_mul_f32 v[24:25], v[24:25], v[130:131] op_sel_hi:[1,0]
	v_mul_f32_e32 v35, v35, v35
	v_cvt_pk_bf16_f32 v33, v33, v34
	v_cvt_pk_bf16_f32 v34, v40, v37
	v_addc_co_u32_e32 v37, vcc, 0, v49, vcc
	s_add_u32 s22, s11, s22
	v_pk_mul_f32 v[28:29], v[28:29], v[130:131] op_sel_hi:[1,0]
	v_pk_mul_f32 v[26:27], v[26:27], v[130:131] op_sel_hi:[1,0]
	v_max_f32_e32 v24, 0, v24
	v_cvt_pk_bf16_f32 v35, v38, v35
	global_store_dwordx4 v[36:37], v[32:35], off
	s_addc_u32 s23, s13, s23
	v_pk_mul_f32 v[30:31], v[30:31], v[130:131] op_sel_hi:[1,0]
	v_mul_f32_e32 v34, v24, v24
	v_max_f32_e32 v24, 0, v29
	v_max_f32_e32 v25, 0, v25
	v_max_f32_e32 v26, 0, v26
	v_lshl_add_u64 v[32:33], s[22:23], 0, v[140:141]
	v_max_f32_e32 v28, 0, v28
	v_mul_f32_e32 v24, v24, v24
	v_mul_f32_e32 v29, v25, v25
	v_max_f32_e32 v25, 0, v30
	v_mul_f32_e32 v30, v26, v26
	v_max_f32_e32 v26, 0, v31
	v_max_f32_e32 v27, 0, v27
	v_pk_mul_f32 v[16:17], v[16:17], v[130:131] op_sel_hi:[1,0]
	v_lshl_add_u64 v[32:33], v[32:33], 0, v[152:153]
	v_mul_f32_e32 v28, v28, v28
	v_mul_f32_e32 v25, v25, v25
	v_mul_f32_e32 v26, v26, v26
	v_mul_f32_e32 v27, v27, v27
	v_cvt_pk_bf16_f32 v24, v28, v24
	v_pk_mul_f32 v[20:21], v[20:21], v[130:131] op_sel_hi:[1,0]
	v_pk_mul_f32 v[18:19], v[18:19], v[130:131] op_sel_hi:[1,0]
	v_max_f32_e32 v16, 0, v16
	s_or_b32 s18, s18, 0x1600
	v_cvt_pk_bf16_f32 v25, v25, v26
	v_cvt_pk_bf16_f32 v26, v34, v29
	v_cvt_pk_bf16_f32 v27, v30, v27
	global_store_dwordx4 v[32:33], v[24:27], off
	v_pk_mul_f32 v[22:23], v[22:23], v[130:131] op_sel_hi:[1,0]
	v_max_f32_e32 v20, 0, v20
	v_mul_f32_e32 v24, v16, v16
	v_max_f32_e32 v16, 0, v21
	v_max_f32_e32 v17, 0, v17
	v_max_f32_e32 v18, 0, v18
	s_add_u32 s20, s18, s20
	v_mul_f32_e32 v20, v20, v20
	v_mul_f32_e32 v16, v16, v16
	v_mul_f32_e32 v21, v17, v17
	v_max_f32_e32 v17, 0, v22
	v_mul_f32_e32 v22, v18, v18
	v_max_f32_e32 v18, 0, v23
	s_addc_u32 s21, 0, s21
	v_mul_f32_e32 v17, v17, v17
	v_mul_f32_e32 v18, v18, v18
	v_max_f32_e32 v19, 0, v19
	v_cvt_pk_bf16_f32 v16, v20, v16
	v_add_co_u32_e32 v20, vcc, s48, v32
	s_lshl_b64 s[20:21], s[20:21], 10
	v_pk_mul_f32 v[8:9], v[8:9], v[128:129] op_sel_hi:[1,0]
	v_mul_f32_e32 v19, v19, v19
	v_cvt_pk_bf16_f32 v17, v17, v18
	v_cvt_pk_bf16_f32 v18, v24, v21
	v_addc_co_u32_e32 v21, vcc, 0, v33, vcc
	s_add_u32 s20, s11, s20
	v_pk_mul_f32 v[12:13], v[12:13], v[128:129] op_sel_hi:[1,0]
	v_pk_mul_f32 v[10:11], v[10:11], v[128:129] op_sel_hi:[1,0]
	v_max_f32_e32 v8, 0, v8
	v_cvt_pk_bf16_f32 v19, v22, v19
	global_store_dwordx4 v[20:21], v[16:19], off
	s_addc_u32 s21, s13, s21
	v_pk_mul_f32 v[14:15], v[14:15], v[128:129] op_sel_hi:[1,0]
	v_mul_f32_e32 v18, v8, v8
	v_max_f32_e32 v8, 0, v13
	v_max_f32_e32 v9, 0, v9
	v_max_f32_e32 v10, 0, v10
	v_lshl_add_u64 v[16:17], s[20:21], 0, v[140:141]
	v_max_f32_e32 v12, 0, v12
	v_mul_f32_e32 v8, v8, v8
	v_mul_f32_e32 v13, v9, v9
	v_max_f32_e32 v9, 0, v14
	v_mul_f32_e32 v14, v10, v10
	v_max_f32_e32 v10, 0, v15
	v_max_f32_e32 v11, 0, v11
	v_pk_mul_f32 v[0:1], v[0:1], v[128:129] op_sel_hi:[1,0]
	v_lshl_add_u64 v[16:17], v[16:17], 0, v[152:153]
	v_mul_f32_e32 v12, v12, v12
	v_mul_f32_e32 v9, v9, v9
	v_mul_f32_e32 v10, v10, v10
	v_mul_f32_e32 v11, v11, v11
	v_cvt_pk_bf16_f32 v8, v12, v8
	v_pk_mul_f32 v[4:5], v[4:5], v[128:129] op_sel_hi:[1,0]
	v_pk_mul_f32 v[2:3], v[2:3], v[128:129] op_sel_hi:[1,0]
	v_max_f32_e32 v0, 0, v0
	v_cvt_pk_bf16_f32 v9, v9, v10
	v_cvt_pk_bf16_f32 v10, v18, v13
	v_cvt_pk_bf16_f32 v11, v14, v11
	global_store_dwordx4 v[16:17], v[8:11], off
	v_pk_mul_f32 v[6:7], v[6:7], v[128:129] op_sel_hi:[1,0]
	v_max_f32_e32 v4, 0, v4
	v_mul_f32_e32 v8, v0, v0
	v_max_f32_e32 v0, 0, v5
	v_max_f32_e32 v1, 0, v1
	v_max_f32_e32 v2, 0, v2
	v_mul_f32_e32 v4, v4, v4
	v_mul_f32_e32 v0, v0, v0
	v_mul_f32_e32 v5, v1, v1
	v_max_f32_e32 v1, 0, v6
	v_mul_f32_e32 v6, v2, v2
	v_max_f32_e32 v2, 0, v7
	v_mul_f32_e32 v1, v1, v1
	v_mul_f32_e32 v2, v2, v2
	v_cvt_pk_bf16_f32 v0, v4, v0
	v_add_co_u32_e32 v4, vcc, 0x1000, v16
	v_max_f32_e32 v3, 0, v3
	v_cvt_pk_bf16_f32 v1, v1, v2
	v_cvt_pk_bf16_f32 v2, v8, v5
	s_nop 0
	v_addc_co_u32_e32 v5, vcc, 0, v17, vcc
	v_mul_f32_e32 v3, v3, v3
	s_andn2_b64 vcc, exec, s[2:3]
	s_mov_b64 s[2:3], -1
	v_cvt_pk_bf16_f32 v3, v6, v3
	global_store_dwordx4 v[4:5], v[0:3], off
	s_cbranch_vccnz .LBB0_1535
	s_andn2_b64 vcc, exec, s[6:7]
	s_cbranch_vccnz .LBB0_1534
	s_barrier
	s_branch .LBB0_1534
